# mLSTM and SSD gate-vector preparation: 64-lane prefix sum and prefix max by DPP row_shr and row_bcast steps instead of six ds_bpermute round trips each
# speedup vs baseline: 1.0071x; 1.0032x over previous
.LBB0_441:
	s_or_b64 exec, exec, s[40:41]
	v_mbcnt_hi_u32_b32 v46, -1, v206
	v_add_f32_e32 v1, v2, v3
	v_mul_f32_e64 v1, v1, -v77
	s_mul_i32 s40, s26, 0x610
	s_add_i32 s70, s40, 0
	s_add_i32 s70, s70, 0x16000
	v_lshl_add_u32 v48, v78, 2, s70
	s_nop 1
	v_add_f32_dpp v1, v1, v1 row_shr:1 row_mask:0xf bank_mask:0xf
	s_nop 1
	v_add_f32_dpp v1, v1, v1 row_shr:2 row_mask:0xf bank_mask:0xf
	s_nop 1
	v_add_f32_dpp v1, v1, v1 row_shr:4 row_mask:0xf bank_mask:0xf
	s_nop 1
	v_add_f32_dpp v1, v1, v1 row_shr:8 row_mask:0xf bank_mask:0xf
	s_nop 1
	v_add_f32_dpp v1, v1, v1 row_bcast:15 row_mask:0xa bank_mask:0xf
	s_nop 1
	v_add_f32_dpp v1, v1, v1 row_bcast:31 row_mask:0xc bank_mask:0xf
	v_mov_b32_e32 v45, v1
	v_lshl_or_b32 v1, v46, 2, v211
	ds_bpermute_b32 v1, v1, v45
	v_fma_f32 v44, v77, v3, v45
	ds_write2st64_b64 v48, v[44:45], v[2:3] offset1:1
	s_waitcnt lgkmcnt(1)
	v_sub_f32_e32 v46, v1, v44
	v_sub_f32_e32 v47, v1, v45
	v_mul_f32_e32 v46, 0x3fb8aa3b, v46
	v_mul_f32_e32 v47, 0x3fb8aa3b, v47
	v_exp_f32_e32 v46, v46
	v_exp_f32_e32 v47, v47
	s_nop 0
	v_pk_mul_f32 v[2:3], v[2:3], v[46:47]
	ds_write_b64 v48, v[2:3] offset:1024
	s_and_saveexec_b64 s[40:41], s[50:51]
	s_cbranch_execz .LBB0_443
	v_mul_f32_e32 v1, 0x3fb8aa3b, v1
	v_exp_f32_e32 v1, v1
	v_mov_b32_e32 v2, s70
	ds_write_b32 v2, v1 offset:1536

; DI unsigned pk2(float lo, float hi) { const f2_t v = {lo, hi}; const bf2_t r = __builtin_convertvector(v, bf2_t); return __builtin_bit_cast(unsigned, r); }
;     DI bf16_t* fOUTS() const { return (bf16_t*)(ws + WS_OUTS); }
; #define ML_GLOAD(chx) do { const int s0_ = (chx) * 128 + 2 * lane, t0_ = dir ? S - 1 - s0_ : s0_, t1_ = dir ? t0_ - 1 : t0_ + 1; \
;         gn0 = Sb[(size_t)t0_ * 32 + dir * 4 + head]; gn1 = Sb[(size_t)t0_ * 32 + 8 + dir * 4 + head]; gn2 = Sb[(size_t)t1_ * 32 + dir * 4 + head]; gn3 = Sb[(size_t)t1_ * 32 + 8 + dir * 4 + head]; } while (0)
; DI void mlstm_item(const Params& p, const Ctx& c, int l, int S, int tokbase, int dir, int head, int eh) {
;     ...
;             const float den = __shfl(accN[4][0], lr), inv = 1.f / fmaxf(fabsf(den), em);
;             const int sidx = ch * 128 + w * 16 + lr, tok = dir ? S - 1 - sidx : sidx;
;             bf16_t* op = c.fOUTS() + (size_t)(tokbase + tok) * OLD + 512 + dir * 512 + head * 128 + eh * 64 + lg * 4;
; #pragma unroll
;             for (int et = 0; et < 4; ++et) { u32x2 o; o.x = pk2(accN[et][0] * inv, accN[et][1] * inv); o.y = pk2(accN[et][2] * inv, accN[et][3] * inv); *(u32x2*)(op + et * 16) = o; }
;         }
;         if (w == 0 && ch + 1 < nch) { ML_PREP(par ^ 1); if (ch + 2 < nch) ML_GLOAD(ch + 2); }
.LBB0_490:
	s_nop 4
	ds_bpermute_b32 v26, v124, v94
	v_max_f32_e32 v27, v113, v113
	v_lshl_add_u32 v29, s24, 7, v118
	s_mov_b32 s39, s75
	s_mov_b32 s67, s75
	s_waitcnt lgkmcnt(0)
	v_max_f32_e64 v26, |v26|, |v26|
	v_max_f32_e32 v26, v26, v27
	v_div_scale_f32 v27, vcc, v26, v26, 1.0
	v_rcp_f32_e32 v28, v27
	v_div_scale_f32 v30, vcc, 1.0, v26, 1.0
	v_mov_b32_e32 v113, v0
	v_fma_f32 v31, -v27, v28, 1.0
	v_fmac_f32_e32 v28, v31, v28
	v_mul_f32_e32 v31, v30, v28
	v_fma_f32 v32, -v27, v31, v30
	v_fmac_f32_e32 v31, v32, v28
	v_fma_f32 v27, -v27, v31, v30
	v_div_fmas_f32 v27, v27, v28, v31
	v_div_fixup_f32 v26, v27, v26, 1.0
	v_xad_u32 v27, v29, -1, s30
	v_cndmask_b32_e64 v27, v27, v29, s[42:43]
	v_add_u32_e32 v27, s36, v27
	v_mov_b64_e32 v[28:29], s[92:93]
	v_mad_i64_i32 v[28:29], vcc, v27, s22, v[28:29]
	v_lshl_add_u64 v[28:29], v[28:29], 0, s[74:75]
	v_lshl_add_u64 v[28:29], v[28:29], 0, s[38:39]
	v_lshl_add_u64 v[28:29], v[28:29], 0, s[66:67]
	v_lshl_add_u64 v[28:29], v[28:29], 0, v[112:113]
	s_mov_b64 s[84:85], 0x10400400
	v_lshl_add_u64 v[30:31], v[28:29], 0, s[84:85]
	v_pk_mul_f32 v[32:33], v[90:91], v[26:27] op_sel_hi:[1,0]
	v_pk_mul_f32 v[34:35], v[92:93], v[26:27] op_sel_hi:[1,0]
	v_add_co_u32_e32 v28, vcc, s79, v28
	v_cvt_pk_bf16_f32 v32, v32, v33
	v_cvt_pk_bf16_f32 v33, v34, v35
	v_addc_co_u32_e32 v29, vcc, 0, v29, vcc
	global_store_dwordx2 v[28:29], v[32:33], off offset:1024
	v_pk_mul_f32 v[28:29], v[86:87], v[26:27] op_sel_hi:[1,0]
	v_pk_mul_f32 v[32:33], v[88:89], v[26:27] op_sel_hi:[1,0]
	v_cvt_pk_bf16_f32 v28, v28, v29
	v_cvt_pk_bf16_f32 v29, v32, v33
	global_store_dwordx2 v[30:31], v[28:29], off offset:32
	v_pk_mul_f32 v[28:29], v[82:83], v[26:27] op_sel_hi:[1,0]
	v_pk_mul_f32 v[32:33], v[84:85], v[26:27] op_sel_hi:[1,0]
	v_cvt_pk_bf16_f32 v28, v28, v29
	v_cvt_pk_bf16_f32 v29, v32, v33
	global_store_dwordx2 v[30:31], v[28:29], off offset:64
	v_pk_mul_f32 v[28:29], v[78:79], v[26:27] op_sel_hi:[1,0]
	v_pk_mul_f32 v[26:27], v[80:81], v[26:27] op_sel_hi:[1,0]
	s_xor_b32 s25, s25, 1
	v_cvt_pk_bf16_f32 v28, v28, v29
	v_cvt_pk_bf16_f32 v29, v26, v27
	s_and_b64 vcc, exec, s[68:69]
	global_store_dwordx2 v[30:31], v[28:29], off offset:96
	s_cbranch_vccz .LBB0_483
	s_andn2_b64 vcc, exec, s[40:41]
	s_cbranch_vccnz .LBB0_483
	v_add_f32_e32 v26, v1, v120
	s_mov_b32 s26, 0xbfb8aa3b
	v_mul_f32_e64 v27, |v26|, s26
	v_exp_f32_e32 v92, v27
	v_add_f32_e32 v27, v1, v121
	v_min_f32_e32 v26, 0, v26
	s_mov_b32 s40, 0x3db504f3
	v_add_f32_e32 v30, 1.0, v92
	v_add_f32_e32 v28, -1.0, v30
	v_sub_f32_e32 v29, v28, v30
	v_sub_f32_e32 v28, v92, v28
	v_add_f32_e32 v29, 1.0, v29
	v_add_f32_e32 v31, v28, v29
	v_mul_f32_e64 v28, |v27|, s26
	v_exp_f32_e32 v93, v28
	v_cvt_f64_f32_e32 v[28:29], v30
	v_frexp_exp_i32_f64_e32 v33, v[28:29]
	s_mov_b32 s26, 0x3f2aaaab
	v_add_f32_e32 v34, 1.0, v93
	v_add_f32_e32 v28, -1.0, v34
	v_sub_f32_e32 v29, v28, v34
	v_add_f32_e32 v29, 1.0, v29
	v_sub_f32_e32 v28, v93, v28
	v_add_f32_e32 v35, v28, v29
	v_frexp_mant_f32_e32 v36, v34
	v_cvt_f64_f32_e32 v[28:29], v34
	v_frexp_exp_i32_f64_e32 v28, v[28:29]
	v_cmp_gt_f32_e32 vcc, s26, v36
	v_frexp_mant_f32_e32 v32, v30
	v_min_f32_e32 v27, 0, v27
	v_subbrev_co_u32_e32 v84, vcc, 0, v28, vcc
	v_cmp_gt_f32_e32 vcc, s26, v32
	s_mov_b32 s26, 0x3e9b6dac
	s_mov_b32 s5, 0x7f800000
	v_subbrev_co_u32_e32 v85, vcc, 0, v33, vcc
	v_sub_u32_e32 v29, 0, v85
	v_ldexp_f32 v28, v30, v29
	v_ldexp_f32 v30, v31, v29
	v_sub_u32_e32 v31, 0, v84
	v_ldexp_f32 v29, v34, v31
	v_pk_add_f32 v[32:33], v[28:29], 1.0 op_sel_hi:[1,0]
	v_ldexp_f32 v31, v35, v31
	v_pk_add_f32 v[34:35], v[32:33], -1.0 op_sel_hi:[1,0]
	v_pk_add_f32 v[40:41], v[28:29], -1.0 op_sel_hi:[1,0]
	v_pk_add_f32 v[34:35], v[28:29], v[34:35] neg_lo:[0,1] neg_hi:[0,1]
	v_pk_add_f32 v[78:79], v[40:41], 1.0 op_sel_hi:[1,0]
	v_pk_add_f32 v[34:35], v[30:31], v[34:35]
	v_pk_add_f32 v[28:29], v[28:29], v[78:79] neg_lo:[0,1] neg_hi:[0,1]
	v_pk_add_f32 v[36:37], v[32:33], v[34:35]
	v_pk_add_f32 v[28:29], v[30:31], v[28:29]
	v_rcp_f32_e32 v38, v36
	v_rcp_f32_e32 v39, v37
	v_pk_add_f32 v[30:31], v[40:41], v[28:29]
	v_pk_add_f32 v[32:33], v[36:37], v[32:33] neg_lo:[0,1] neg_hi:[0,1]
	v_pk_add_f32 v[40:41], v[30:31], v[40:41] neg_lo:[0,1] neg_hi:[0,1]
	v_pk_add_f32 v[32:33], v[34:35], v[32:33] neg_lo:[0,1] neg_hi:[0,1]
	v_pk_mul_f32 v[34:35], v[30:31], v[38:39]
	v_pk_add_f32 v[28:29], v[28:29], v[40:41] neg_lo:[0,1] neg_hi:[0,1]
	v_pk_mul_f32 v[40:41], v[36:37], v[34:35]
	s_nop 0
	v_pk_fma_f32 v[78:79], v[34:35], v[36:37], v[40:41] neg_lo:[0,0,1] neg_hi:[0,0,1]
	s_nop 0
	v_pk_fma_f32 v[78:79], v[34:35], v[32:33], v[78:79]
	s_nop 0
	v_pk_add_f32 v[80:81], v[40:41], v[78:79]
	s_nop 0
	v_pk_add_f32 v[82:83], v[30:31], v[80:81] neg_lo:[0,1] neg_hi:[0,1]
	v_pk_add_f32 v[40:41], v[80:81], v[40:41] neg_lo:[0,1] neg_hi:[0,1]
	v_pk_add_f32 v[30:31], v[30:31], v[82:83] neg_lo:[0,1] neg_hi:[0,1]
	s_nop 0
	v_pk_add_f32 v[30:31], v[30:31], v[80:81] neg_lo:[0,1] neg_hi:[0,1]
	s_nop 0
	v_pk_add_f32 v[28:29], v[28:29], v[30:31]
	v_pk_add_f32 v[30:31], v[40:41], v[78:79] neg_lo:[0,1] neg_hi:[0,1]
	s_nop 0
	v_pk_add_f32 v[28:29], v[30:31], v[28:29]
	s_nop 0
	v_pk_add_f32 v[30:31], v[82:83], v[28:29]
	s_nop 0
	v_pk_mul_f32 v[40:41], v[38:39], v[30:31]
	s_nop 0
	v_pk_mul_f32 v[78:79], v[36:37], v[40:41]
	s_nop 0
	v_pk_fma_f32 v[36:37], v[40:41], v[36:37], v[78:79] neg_lo:[0,0,1] neg_hi:[0,0,1]
	s_nop 0
	v_pk_fma_f32 v[32:33], v[40:41], v[32:33], v[36:37]
	v_pk_add_f32 v[36:37], v[82:83], v[30:31] neg_lo:[0,1] neg_hi:[0,1]
	s_nop 0
	v_pk_add_f32 v[28:29], v[28:29], v[36:37]
	v_pk_add_f32 v[36:37], v[78:79], v[32:33]
	s_nop 0
	v_pk_add_f32 v[80:81], v[30:31], v[36:37] neg_lo:[0,1] neg_hi:[0,1]
	v_pk_add_f32 v[78:79], v[36:37], v[78:79] neg_lo:[0,1] neg_hi:[0,1]
	v_pk_add_f32 v[30:31], v[30:31], v[80:81] neg_lo:[0,1] neg_hi:[0,1]
	s_nop 0
	v_pk_add_f32 v[30:31], v[30:31], v[36:37] neg_lo:[0,1] neg_hi:[0,1]
	s_nop 0
	v_pk_add_f32 v[28:29], v[28:29], v[30:31]
	v_pk_add_f32 v[30:31], v[78:79], v[32:33] neg_lo:[0,1] neg_hi:[0,1]
	s_nop 0
	v_pk_add_f32 v[28:29], v[30:31], v[28:29]
	v_pk_add_f32 v[30:31], v[34:35], v[40:41]
	v_pk_add_f32 v[28:29], v[80:81], v[28:29]
	v_pk_add_f32 v[32:33], v[30:31], v[34:35] neg_lo:[0,1] neg_hi:[0,1]
	v_pk_mul_f32 v[28:29], v[38:39], v[28:29]
	v_pk_add_f32 v[32:33], v[40:41], v[32:33] neg_lo:[0,1] neg_hi:[0,1]
	v_cvt_f32_i32_e32 v35, v84
	v_pk_add_f32 v[28:29], v[32:33], v[28:29]
	v_cvt_f32_i32_e32 v34, v85
	v_pk_add_f32 v[32:33], v[30:31], v[28:29]
	s_nop 0
	v_pk_mul_f32 v[36:37], v[32:33], v[32:33]
	v_pk_add_f32 v[30:31], v[32:33], v[30:31] neg_lo:[0,1] neg_hi:[0,1]
	v_pk_fma_f32 v[38:39], v[36:37], s[26:27], v[166:167] op_sel_hi:[1,0,0]
	s_mov_b32 s26, 0x3f2aaada
	v_pk_add_f32 v[28:29], v[28:29], v[30:31] neg_lo:[0,1] neg_hi:[0,1]
	v_ldexp_f32 v30, v32, 1
	v_pk_fma_f32 v[38:39], v[36:37], v[38:39], s[26:27] op_sel_hi:[1,1,0]
	v_ldexp_f32 v31, v33, 1
	v_pk_mul_f32 v[32:33], v[32:33], v[36:37]
	s_mov_b32 s26, 0x3f317218
	v_pk_mul_f32 v[32:33], v[32:33], v[38:39]
	v_ldexp_f32 v81, v29, 1
	v_pk_add_f32 v[36:37], v[30:31], v[32:33]
	v_ldexp_f32 v28, v28, 1
	v_pk_add_f32 v[30:31], v[36:37], v[30:31] neg_lo:[0,1] neg_hi:[0,1]
	v_pk_mul_f32 v[40:41], v[34:35], s[26:27] op_sel_hi:[1,0]
	v_pk_add_f32 v[30:31], v[32:33], v[30:31] neg_lo:[0,1] neg_hi:[0,1]
	v_mov_b32_e32 v29, v81
	v_pk_fma_f32 v[78:79], v[34:35], s[26:27], v[40:41] op_sel_hi:[1,0,1] neg_lo:[0,0,1] neg_hi:[0,0,1]
	s_mov_b32 s26, 0xb102e308
	v_pk_add_f32 v[38:39], v[28:29], v[30:31]
	v_pk_fma_f32 v[34:35], v[34:35], s[26:27], v[78:79] op_sel_hi:[1,0,1]
	v_mov_b32_e32 v33, v31
	v_mov_b32_e32 v29, v39
	v_mov_b32_e32 v31, v37
	v_pk_add_f32 v[78:79], v[40:41], v[34:35]
	v_mov_b32_e32 v32, v40
	v_mov_b32_e32 v80, v34
	v_pk_add_f32 v[28:29], v[28:29], v[30:31]
	v_pk_add_f32 v[30:31], v[36:37], v[38:39]
	v_pk_add_f32 v[32:33], v[32:33], v[80:81]
	v_mov_b32_e32 v80, v78
	v_mov_b32_e32 v81, v41
	v_mov_b32_e32 v82, v30
	v_mov_b32_e32 v83, v35
	v_mov_b32_e32 v86, v78
	v_mov_b32_e32 v87, v37
	v_mov_b32_e32 v88, v30
	v_mov_b32_e32 v89, v39
	v_pk_add_f32 v[84:85], v[80:81], v[82:83]
	v_pk_add_f32 v[86:87], v[86:87], v[88:89]
	v_pk_add_f32 v[88:89], v[78:79], v[30:31]
	v_pk_add_f32 v[80:81], v[84:85], v[80:81] neg_lo:[0,1] neg_hi:[0,1]
	v_mov_b32_e32 v84, v30
	v_mov_b32_e32 v85, v89
	v_mov_b32_e32 v90, v36
	v_mov_b32_e32 v91, v79
	v_pk_add_f32 v[84:85], v[84:85], v[90:91] neg_lo:[0,1] neg_hi:[0,1]
	v_mov_b32_e32 v90, v78
	v_mov_b32_e32 v91, v89
	v_mov_b32_e32 v41, v85
	v_pk_add_f32 v[40:41], v[90:91], v[40:41] neg_lo:[0,1] neg_hi:[0,1]
	v_pk_add_f32 v[82:83], v[82:83], v[80:81] neg_lo:[0,1] neg_hi:[0,1]
	v_mov_b32_e32 v90, v40
	v_mov_b32_e32 v91, v81
	v_mov_b32_e32 v81, v37
	v_pk_add_f32 v[90:91], v[34:35], v[90:91] neg_lo:[0,1] neg_hi:[0,1]
	v_pk_add_f32 v[80:81], v[86:87], v[80:81] neg_lo:[0,1] neg_hi:[0,1]
	v_mov_b32_e32 v35, v79
	v_pk_add_f32 v[32:33], v[32:33], v[80:81] neg_lo:[0,1] neg_hi:[0,1]
	v_pk_add_f32 v[34:35], v[34:35], v[40:41] neg_lo:[0,1] neg_hi:[0,1]
	v_pk_add_f32 v[28:29], v[28:29], v[84:85] neg_lo:[0,1] neg_hi:[0,1]
	v_pk_add_f32 v[30:31], v[30:31], v[36:37] neg_lo:[0,1] neg_hi:[0,1]
	v_pk_add_f32 v[36:37], v[28:29], v[34:35]
	v_mov_b32_e32 v29, v33
	v_pk_add_f32 v[30:31], v[38:39], v[30:31] neg_lo:[0,1] neg_hi:[0,1]
	v_pk_add_f32 v[38:39], v[82:83], v[32:33]
	v_pk_add_f32 v[28:29], v[90:91], v[28:29]
	v_mov_b32_e32 v35, v83
	v_pk_add_f32 v[28:29], v[28:29], v[34:35] neg_lo:[0,1] neg_hi:[0,1]
	v_mov_b32_e32 v32, v36
	v_mov_b32_e32 v33, v39
	v_pk_add_f32 v[32:33], v[32:33], v[28:29] neg_lo:[0,1] neg_hi:[0,1]
	v_pk_add_f32 v[28:29], v[30:31], v[28:29] neg_lo:[0,1] neg_hi:[0,1]
	v_pk_add_f32 v[32:33], v[34:35], v[32:33] neg_lo:[0,1] neg_hi:[0,1]
	v_pk_add_f32 v[30:31], v[38:39], v[36:37]
	v_pk_add_f32 v[28:29], v[28:29], v[32:33]
	v_pk_add_f32 v[32:33], v[88:89], v[30:31]
	s_mov_b32 s26, 0x7f800000
	v_pk_add_f32 v[34:35], v[32:33], v[88:89] neg_lo:[0,1] neg_hi:[0,1]
	v_cmp_neq_f32_e32 vcc, s26, v92
	v_pk_add_f32 v[30:31], v[30:31], v[34:35] neg_lo:[0,1] neg_hi:[0,1]
	s_mov_b32 s27, 0x33800000
	v_pk_add_f32 v[28:29], v[28:29], v[30:31]
	v_pk_add_f32 v[30:31], v[106:107], v[108:109]
	v_pk_add_f32 v[28:29], v[32:33], v[28:29]
	v_max_f32_e32 v33, v122, v122
	v_cndmask_b32_e32 v28, v209, v28, vcc
	v_cmp_neq_f32_e32 vcc, s26, v93
	s_mov_b32 s26, 0x33800000
	s_nop 0
	v_cndmask_b32_e32 v29, v209, v29, vcc
	v_cmp_ngt_f32_e32 vcc, -1.0, v93
	s_nop 1
	v_cndmask_b32_e32 v29, v210, v29, vcc
	v_cmp_ngt_f32_e32 vcc, -1.0, v92
	s_nop 1
	v_cndmask_b32_e32 v28, v210, v28, vcc
	v_cmp_neq_f32_e32 vcc, -1.0, v92
	s_nop 1
	v_cndmask_b32_e32 v28, v208, v28, vcc
	v_cmp_neq_f32_e32 vcc, -1.0, v93
	s_nop 1
	v_cndmask_b32_e32 v29, v208, v29, vcc
	v_cmp_lt_f32_e64 vcc, |v93|, s26
	s_nop 1
	v_cndmask_b32_e32 v29, v29, v93, vcc
	v_cmp_lt_f32_e64 vcc, |v92|, s26
	s_mul_i32 s26, s25, 0xa10
	s_add_i32 s26, s26, 0
	v_cndmask_b32_e32 v28, v28, v92, vcc
	v_pk_add_f32 v[26:27], v[26:27], v[28:29] neg_lo:[0,1] neg_hi:[0,1]
	s_add_i32 s26, s26, 0x20f00
	v_add_f32_e32 v26, v26, v27
	v_lshl_add_u32 v38, v117, 2, s26
	s_nop 1
	v_add_f32_dpp v26, v26, v26 row_shr:1 row_mask:0xf bank_mask:0xf
	s_nop 1
	v_add_f32_dpp v26, v26, v26 row_shr:2 row_mask:0xf bank_mask:0xf
	s_nop 1
	v_add_f32_dpp v26, v26, v26 row_shr:4 row_mask:0xf bank_mask:0xf
	s_nop 1
	v_add_f32_dpp v26, v26, v26 row_shr:8 row_mask:0xf bank_mask:0xf
	s_nop 1
	v_add_f32_dpp v26, v26, v26 row_bcast:15 row_mask:0xa bank_mask:0xf
	s_nop 1
	v_add_f32_dpp v26, v26, v26 row_bcast:31 row_mask:0xc bank_mask:0xf
	v_mov_b32_e32 v29, v26
	v_sub_f32_e32 v28, v29, v27
	v_pk_add_f32 v[30:31], v[30:31], v[28:29] neg_lo:[0,1] neg_hi:[0,1]
	s_nop 0
	v_max_f32_e32 v26, v30, v31
	s_nop 1
	v_max_f32_dpp v26, v26, v26 row_shr:1 row_mask:0xf bank_mask:0xf
	s_nop 1
	v_max_f32_dpp v26, v26, v26 row_shr:2 row_mask:0xf bank_mask:0xf
	s_nop 1
	v_max_f32_dpp v26, v26, v26 row_shr:4 row_mask:0xf bank_mask:0xf
	s_nop 1
	v_max_f32_dpp v26, v26, v26 row_shr:8 row_mask:0xf bank_mask:0xf
	s_nop 1
	v_max_f32_dpp v26, v26, v26 row_bcast:15 row_mask:0xa bank_mask:0xf
	s_nop 1
	v_max_f32_dpp v26, v26, v26 row_bcast:31 row_mask:0xc bank_mask:0xf
	v_mov_b32_e32 v27, v26
	ds_bpermute_b32 v32, v125, v27
	v_max_f32_e32 v27, v27, v27
	v_max_f32_e32 v33, v33, v27
	ds_bpermute_b32 v27, v119, v33
	ds_bpermute_b32 v26, v119, v29
	s_waitcnt lgkmcnt(2)
	v_cndmask_b32_e64 v32, v32, v208, s[44:45]
	v_max3_f32 v32, v122, v32, v30
	v_sub_f32_e32 v34, v122, v32
	s_waitcnt lgkmcnt(1)
	v_sub_f32_e32 v36, v30, v27
	v_sub_f32_e32 v37, v31, v27
	v_sub_f32_e32 v35, v122, v33
	v_add_f32_e32 v28, v28, v32
	v_add_f32_e32 v29, v29, v33
	v_mul_f32_e32 v36, 0x3fb8aa3b, v36
	v_mul_f32_e32 v37, 0x3fb8aa3b, v37
	v_mul_f32_e32 v34, 0x3fb8aa3b, v34
	v_mul_f32_e32 v35, 0x3fb8aa3b, v35
	v_mul_f32_e32 v28, 0xbfb8aa3b, v28
	v_mul_f32_e32 v29, 0xbfb8aa3b, v29
	v_exp_f32_e32 v36, v36
	v_exp_f32_e32 v37, v37
	v_exp_f32_e32 v34, v34
	v_exp_f32_e32 v35, v35
	v_exp_f32_e32 v28, v28
	v_exp_f32_e32 v29, v29
	ds_write2st64_b64 v38, v[30:31], v[32:33] offset1:1
	ds_write2st64_b64 v38, v[34:35], v[28:29] offset0:2 offset1:3
	v_pk_mul_f32 v[28:29], v[36:37], s[40:41] op_sel_hi:[1,0]
	ds_write_b64 v38, v[28:29] offset:2048
	s_and_saveexec_b64 s[40:41], s[44:45]
	s_cbranch_execz .LBB0_494
	v_sub_f32_e32 v28, v122, v27
	v_mul_f32_e32 v28, 0x3fb8aa3b, v28
	v_exp_f32_e32 v28, v28
	v_mov_b32_e32 v29, s26
	ds_write_b32 v29, v28 offset:2560
